# late out-proj-phase gate/up weight conversion stores write-through (sc1), on top of PH7 epilogue sc1 and PH8 epilogue nt
# baseline (speedup 1.0000x reference)
; __device__ __forceinline__ unsigned cvt_pk_bf16(float lo, float hi) { const f32x2 v = {lo, hi}; const bf16x2_t b = __builtin_convertvector(v, bf16x2_t); return __builtin_bit_cast(unsigned, b); }
; template <int JOB> __device__ __forceinline__ void conv_item(const Ptrs& P, int item, int lane) {
;     ...
;     for (int j = 0; j < 4; ++j) { u32x4 o0, o1;
;         o0.x = cvt_pk_bf16(v[0][j], v[1][j]); o0.y = cvt_pk_bf16(v[2][j], v[3][j]); o0.z = cvt_pk_bf16(v[4][j], v[5][j]); o0.w = cvt_pk_bf16(v[6][j], v[7][j]);
;         o1.x = cvt_pk_bf16(v[8][j], v[9][j]); o1.y = cvt_pk_bf16(v[10][j], v[11][j]); o1.z = cvt_pk_bf16(v[12][j], v[13][j]); o1.w = cvt_pk_bf16(v[14][j], v[15][j]);
;         bf16* d = WT + (size_t)(n0 + j) * K + kk; *(u32x4*)d = o0; *(u32x4*)(d + 64) = o1; }
; __global__ void __launch_bounds__(NWAVES * 64, 2) hybrid_fwd(Args args) {
;     ...
;         auto ffn_conv = [&]() { for (int r = gw; r < conv_items(2048, 11264); r += NGW) conv_item<J_WFFN>(P, r, lane); };
.LBB0_920:
	v_ashrrev_i32_e32 v69, 31, v68
	v_lshl_add_u64 v[70:71], v[70:71], 1, s[6:7]
	v_lshlrev_b64 v[82:83], 12, v[68:69]
	s_waitcnt vmcnt(14)
	v_cvt_pk_bf16_f32 v74, v2, v6
	s_waitcnt vmcnt(12)
	v_cvt_pk_bf16_f32 v75, v10, v14
	s_waitcnt vmcnt(10)
	v_cvt_pk_bf16_f32 v76, v18, v22
	s_waitcnt vmcnt(8)
	v_cvt_pk_bf16_f32 v77, v26, v30
	v_lshl_add_u64 v[82:83], v[70:71], 0, v[82:83]
	v_add_u32_e32 v2, 1, v68
	s_waitcnt vmcnt(6)
	v_cvt_pk_bf16_f32 v78, v34, v38
	s_waitcnt vmcnt(4)
	v_cvt_pk_bf16_f32 v79, v42, v46
	s_waitcnt vmcnt(2)
	v_cvt_pk_bf16_f32 v80, v50, v54
	s_waitcnt vmcnt(0)
	v_cvt_pk_bf16_f32 v81, v58, v62
	global_store_dwordx4 v[82:83], v[74:77], off sc1
	global_store_dwordx4 v[82:83], v[78:81], off offset:128 sc1
	v_add_u32_e32 v10, 3, v68
	v_cvt_pk_bf16_f32 v74, v3, v7
	v_ashrrev_i32_e32 v3, 31, v2
	v_lshlrev_b64 v[2:3], 12, v[2:3]
	v_cvt_pk_bf16_f32 v75, v11, v15
	v_cvt_pk_bf16_f32 v76, v19, v23
	v_cvt_pk_bf16_f32 v77, v27, v31
	v_lshl_add_u64 v[2:3], v[70:71], 0, v[2:3]
	v_cvt_pk_bf16_f32 v78, v35, v39
	v_cvt_pk_bf16_f32 v79, v43, v47
	v_cvt_pk_bf16_f32 v80, v51, v55
	v_cvt_pk_bf16_f32 v81, v59, v63
	global_store_dwordx4 v[2:3], v[74:77], off sc1
	global_store_dwordx4 v[2:3], v[78:81], off offset:128 sc1
	v_add_u32_e32 v2, 2, v68
	v_ashrrev_i32_e32 v3, 31, v2
	v_lshlrev_b64 v[2:3], 12, v[2:3]
	v_ashrrev_i32_e32 v11, 31, v10
	v_cvt_pk_bf16_f32 v74, v4, v8
	v_cvt_pk_bf16_f32 v75, v12, v16
	v_cvt_pk_bf16_f32 v76, v20, v24
	v_cvt_pk_bf16_f32 v77, v28, v32
	v_lshl_add_u64 v[2:3], v[70:71], 0, v[2:3]
	v_lshlrev_b64 v[10:11], 12, v[10:11]
	s_add_i32 s29, s29, s84
	s_add_i32 s10, s10, s11
	v_cvt_pk_bf16_f32 v78, v36, v40
	v_cvt_pk_bf16_f32 v79, v44, v48
	v_cvt_pk_bf16_f32 v80, v52, v56
	v_cvt_pk_bf16_f32 v81, v60, v64
	global_store_dwordx4 v[2:3], v[74:77], off sc1
	global_store_dwordx4 v[2:3], v[78:81], off offset:128 sc1
	v_cvt_pk_bf16_f32 v2, v5, v9
	v_cvt_pk_bf16_f32 v3, v13, v17
	v_cvt_pk_bf16_f32 v4, v21, v25
	v_cvt_pk_bf16_f32 v5, v29, v33
	v_lshl_add_u64 v[10:11], v[70:71], 0, v[10:11]
	s_cmpk_lt_i32 s29, 0x1600
	v_add_u32_e32 v73, s3, v73
	v_cvt_pk_bf16_f32 v6, v37, v41
	v_cvt_pk_bf16_f32 v7, v45, v49
	v_cvt_pk_bf16_f32 v8, v53, v57
	v_cvt_pk_bf16_f32 v9, v61, v65
	global_store_dwordx4 v[10:11], v[2:5], off sc1
	global_store_dwordx4 v[10:11], v[6:9], off offset:128 sc1
	s_cbranch_scc0 .LBB0_927
